# attention items ordered by head within each workgroup so units of the same head run at about the same time on an XCD (K/V L2 reuse)
# speedup vs baseline: 1.0099x; 1.0014x over previous
.Ltbl:
	s_and_b32 s0, s73, 15
	s_mov_b32 s100, 0x40114d22
	s_cmp_eq_u32 s0, 1
	s_cselect_b32 s100, 0x403ffc81, s100
	s_cmp_eq_u32 s0, 2
	s_cselect_b32 s100, 0x407e4a89, s100
	s_cmp_eq_u32 s0, 3
	s_cselect_b32 s100, 0x401be760, s100
	s_cmp_eq_u32 s0, 4
	s_cselect_b32 s100, 0x40365333, s100
	s_cmp_eq_u32 s0, 5
	s_cselect_b32 s100, 0x401ef9b8, s100
	s_cmp_eq_u32 s0, 6
	s_cselect_b32 s100, 0x405e77b0, s100
	s_cmp_eq_u32 s0, 7
	s_cselect_b32 s100, 0x40f5c440, s100
	s_cmp_eq_u32 s0, 8
	s_cselect_b32 s100, 0x4017c4b1, s100
	s_cmp_eq_u32 s0, 9
	s_cselect_b32 s100, 0x40dc3e99, s100
	s_cmp_eq_u32 s0, 10
	s_cselect_b32 s100, 0x40b63428, s100
	s_cmp_eq_u32 s0, 11
	s_cselect_b32 s100, 0x40595d58, s100
	s_cmp_eq_u32 s0, 12
	s_cselect_b32 s100, 0x403acac8, s100
	s_cmp_eq_u32 s0, 13
	s_cselect_b32 s100, 0x406fb0a1, s100
	s_cmp_eq_u32 s0, 14
	s_cselect_b32 s100, 0x40d932a9, s100
	s_cmp_eq_u32 s0, 15
	s_cselect_b32 s100, 0x40b8b6b9, s100
	s_mov_b32 s74, 0
